# lever 7.3/T21: MLA unit epilogue row stores widened with v_permlane32_swap (8 x dwordx2 -> 4 x dwordx4 per lane)
# speedup vs baseline: 1.0102x; 1.0102x over previous
; template <int DQK, int DV, int RH, bool NEGM> ...
;     ...
; #pragma unroll
;     for (int hh = 0; hh < RH; ++hh) {
;         float l = (lacc[hh][0] + lacc[hh][1]) + (lacc[hh][2] + lacc[hh][3]); l += __shfl_xor(l, 32);
;         const float inv = 1.f / l;
;         const size_t ro = (size_t)(wid * 32 * RH + hh * 32 + r32) * zpitch;
.LBB0_862:
	v_exp_f32_e32 v66, v48
	v_exp_f32_e32 v68, v49
	v_exp_f32_e32 v67, v50
	v_exp_f32_e32 v69, v51
	v_exp_f32_e32 v50, v52
	v_exp_f32_e32 v52, v53
	v_exp_f32_e32 v51, v54
	v_exp_f32_e32 v53, v55
	v_cvt_pk_bf16_f32 v70, v66, v68
	v_cvt_pk_bf16_f32 v71, v67, v69
	v_cvt_pk_bf16_f32 v72, v50, v52
	v_cvt_pk_bf16_f32 v73, v51, v53
	s_mul_i32 s6, s39, 0x2800
	s_mul_hi_u32 s7, s38, 0x2800
	s_waitcnt lgkmcnt(7)
	v_mfma_f32_32x32x16_bf16 v[16:31], v[108:111], v[70:73], v[16:31]
	s_add_i32 s7, s7, s6
	s_mulk_i32 s38, 0x2800
	s_add_u32 s6, s10, s38
	v_exp_f32_e32 v74, v56
	v_exp_f32_e32 v76, v57
	v_exp_f32_e32 v75, v58
	v_exp_f32_e32 v77, v59
	s_waitcnt lgkmcnt(3)
	v_mfma_f32_32x32x16_bf16 v[0:15], v[112:115], v[70:73], v[0:15]
	v_exp_f32_e32 v58, v60
	v_exp_f32_e32 v60, v61
	v_exp_f32_e32 v59, v62
	v_exp_f32_e32 v61, v63
	s_addc_u32 s7, s11, s7
	s_lshl_b32 s8, s46, 1
	s_add_u32 s6, s6, s8
	s_addc_u32 s7, s7, 0
	s_add_u32 s6, s6, 0x3000400
	v_cvt_pk_bf16_f32 v54, v74, v76
	v_cvt_pk_bf16_f32 v55, v75, v77
	v_cvt_pk_bf16_f32 v56, v58, v60
	v_cvt_pk_bf16_f32 v57, v59, v61
	s_addc_u32 s7, s7, 0
	v_lshlrev_b32_e32 v48, 2, v165
	v_mfma_f32_32x32x16_bf16 v[16:31], v[104:107], v[54:57], v[16:31]
	v_mov_b64_e32 v[62:63], s[6:7]
	v_mad_u64_u32 v[62:63], s[6:7], v164, s60, v[62:63]
	v_ashrrev_i32_e32 v49, 31, v48
	v_lshl_add_u64 v[48:49], v[48:49], 1, v[62:63]
	v_exp_f32_e32 v70, v32
	v_exp_f32_e32 v72, v33
	s_waitcnt lgkmcnt(2)
	v_mfma_f32_32x32x16_bf16 v[0:15], v[100:103], v[54:57], v[0:15]
	v_exp_f32_e32 v71, v34
	v_exp_f32_e32 v73, v35
	v_exp_f32_e32 v36, v36
	v_exp_f32_e32 v78, v37
	v_exp_f32_e32 v37, v38
	v_exp_f32_e32 v79, v39
	s_waitcnt lgkmcnt(0)
	s_barrier
	v_mov_b32_e32 v241, 0x10000
	ds_read_b32 v241, v241
	s_waitcnt lgkmcnt(0)
	v_readfirstlane_b32 s67, v241
	s_nop 0
	s_cmp_lg_u32 s67, 0
	s_cbranch_scc1 .Lmla_redo
; #define GAS __attribute__((address_space(1)))
; __device__ __forceinline__ float bf_lo(unsigned w) { return __uint_as_float(w << 16); }
; __device__ __forceinline__ float bf_hi(unsigned w) { return __uint_as_float(w & 0xffff0000u); }
; template <int DQK, int DV, int RH, bool NEGM> ...
;     ...
; #pragma unroll
;     for (int hh = 0; hh < RH; ++hh) {
;         float l = (lacc[hh][0] + lacc[hh][1]) + (lacc[hh][2] + lacc[hh][3]); l += __shfl_xor(l, 32);
;         const float inv = 1.f / l;
;         const size_t ro = (size_t)(wid * 32 * RH + hh * 32 + r32) * zpitch;
; #pragma unroll
;         for (int dt = 0; dt < DV / 32; ++dt)
; #pragma unroll
;             for (int i = 0; i < 4; ++i) {
;                 const int c = dt * 32 + 8 * i + 4 * hi;
;                 const u32x2 zw = *(const GAS u32x2*)(ZI + ro + c);
;                 u32x2 w;
;                 w.x = pk2(o[hh][dt][4 * i + 0] * inv * bf_lo(zw.x), o[hh][dt][4 * i + 1] * inv * bf_hi(zw.x));
;                 w.y = pk2(o[hh][dt][4 * i + 2] * inv * bf_lo(zw.y), o[hh][dt][4 * i + 3] * inv * bf_hi(zw.y));
;                 *(GAS u32x2*)(ZO + ro + c) = w;
;             }
	global_load_dwordx2 v[62:63], v[48:49], off
	global_load_dwordx2 v[54:55], v[48:49], off offset:16
	global_load_dwordx2 v[56:57], v[48:49], off offset:32
	v_exp_f32_e32 v38, v40
	v_exp_f32_e32 v40, v41
	v_exp_f32_e32 v39, v42
	v_exp_f32_e32 v41, v43
	v_exp_f32_e32 v42, v44
	v_exp_f32_e32 v44, v45
	v_exp_f32_e32 v43, v46
	v_exp_f32_e32 v45, v47
	v_cvt_pk_bf16_f32 v32, v70, v72
	v_cvt_pk_bf16_f32 v33, v71, v73
	v_cvt_pk_bf16_f32 v34, v36, v78
	v_cvt_pk_bf16_f32 v35, v37, v79
	v_pk_add_f32 v[36:37], v[50:51], v[36:37]
	v_pk_add_f32 v[50:51], v[66:67], v[70:71]
	v_mfma_f32_32x32x16_bf16 v[16:31], v[96:99], v[32:35], v[16:31]
	v_add_f32_e64 v52, v52, v78
	v_add_f32_e64 v53, v53, v79
	v_add_f32_e64 v50, v150, v50
	v_add_f32_e64 v51, v151, v51
	global_load_dwordx2 v[46:47], v[48:49], off offset:48
	v_pk_add_f32 v[36:37], v[36:37], v[50:51]
	s_add_i32 s61, s61, s18
	s_cmpk_gt_i32 s61, 0x3ff
	v_mfma_f32_32x32x16_bf16 v[0:15], v[92:95], v[32:35], v[0:15]
	v_cvt_pk_bf16_f32 v34, v42, v44
	v_cvt_pk_bf16_f32 v35, v43, v45
	v_add_f32_e64 v44, v60, v44
	v_add_f32_e64 v45, v61, v45
	v_add_f32_e64 v60, v68, v72
	v_add_f32_e64 v61, v69, v73
	v_cvt_pk_bf16_f32 v32, v38, v40
	v_pk_add_f32 v[60:61], v[64:65], v[60:61]
	v_cvt_pk_bf16_f32 v33, v39, v41
	v_pk_add_f32 v[40:41], v[76:77], v[40:41]
	v_pk_add_f32 v[52:53], v[52:53], v[60:61]
	v_pk_add_f32 v[38:39], v[74:75], v[38:39]
	v_pk_add_f32 v[40:41], v[40:41], v[52:53]
	v_pk_add_f32 v[42:43], v[58:59], v[42:43]
	v_pk_add_f32 v[36:37], v[38:39], v[36:37]
	v_pk_add_f32 v[40:41], v[44:45], v[40:41]
	v_pk_add_f32 v[36:37], v[42:43], v[36:37]
	global_load_dwordx2 v[44:45], v[48:49], off offset:64
	v_pk_add_f32 v[36:37], v[36:37], v[40:41]
	v_mfma_f32_32x32x16_bf16 v[16:31], v[88:91], v[32:35], v[16:31]
	v_add_f32_e32 v38, v36, v37
	ds_bpermute_b32 v39, v162, v38
	global_load_dwordx2 v[36:37], v[48:49], off offset:80
	s_waitcnt lgkmcnt(0)
	v_add_f32_e32 v38, v38, v39
	v_div_scale_f32 v39, s[6:7], v38, v38, 1.0
	v_rcp_f32_e32 v40, v39
	v_mfma_f32_32x32x16_bf16 v[0:15], v[84:87], v[32:35], v[0:15]
	global_load_dwordx2 v[32:33], v[48:49], off offset:96
	v_fma_f32 v34, -v39, v40, 1.0
	v_fmac_f32_e32 v40, v34, v40
	v_div_scale_f32 v34, vcc, 1.0, v38, 1.0
	v_mul_f32_e32 v35, v34, v40
	v_fma_f32 v41, -v39, v35, v34
	v_fmac_f32_e32 v35, v41, v40
	v_fma_f32 v34, -v39, v35, v34
	v_div_fmas_f32 v39, v34, v40, v35
	global_load_dwordx2 v[34:35], v[48:49], off offset:112
	v_div_fixup_f32 v38, v39, v38, 1.0
	v_pk_mul_f32 v[16:17], v[16:17], v[38:39] op_sel_hi:[1,0]
	v_pk_mul_f32 v[18:19], v[18:19], v[38:39] op_sel_hi:[1,0]
	v_pk_mul_f32 v[0:1], v[0:1], v[38:39] op_sel_hi:[1,0]
	v_pk_mul_f32 v[2:3], v[2:3], v[38:39] op_sel_hi:[1,0]
	v_lshrrev_b32_e32 v106, 5, v184
	v_lshlrev_b32_e32 v106, 3, v106
	v_mov_b32_e32 v107, 0
	v_lshl_add_u64 v[242:243], v[48:49], 0, v[106:107]
	s_waitcnt vmcnt(7)
	v_lshlrev_b32_e32 v40, 16, v62
	v_and_b32_e32 v41, 0xffff0000, v62
	v_pk_mul_f32 v[16:17], v[16:17], v[40:41]
	v_lshlrev_b32_e32 v40, 16, v63
	v_and_b32_e32 v41, 0xffff0000, v63
	v_pk_mul_f32 v[18:19], v[18:19], v[40:41]
	v_cvt_pk_bf16_f32 v244, v16, v17
	v_cvt_pk_bf16_f32 v245, v18, v19
	v_pk_mul_f32 v[16:17], v[20:21], v[38:39] op_sel_hi:[1,0]
	s_waitcnt vmcnt(6)
	v_lshlrev_b32_e32 v18, 16, v54
	v_and_b32_e32 v19, 0xffff0000, v54
	v_pk_mul_f32 v[16:17], v[16:17], v[18:19]
	v_pk_mul_f32 v[18:19], v[22:23], v[38:39] op_sel_hi:[1,0]
	v_lshlrev_b32_e32 v20, 16, v55
	v_and_b32_e32 v21, 0xffff0000, v55
	v_pk_mul_f32 v[18:19], v[18:19], v[20:21]
	v_cvt_pk_bf16_f32 v246, v16, v17
	v_cvt_pk_bf16_f32 v247, v18, v19
	s_nop 1
	v_permlane32_swap_b32_e32 v244, v246
	v_permlane32_swap_b32_e32 v245, v247
	global_store_dwordx4 v[242:243], v[244:247], off
	v_pk_mul_f32 v[16:17], v[24:25], v[38:39] op_sel_hi:[1,0]
	s_waitcnt vmcnt(6)
	v_lshlrev_b32_e32 v18, 16, v56
	v_and_b32_e32 v19, 0xffff0000, v56
	v_pk_mul_f32 v[16:17], v[16:17], v[18:19]
	v_pk_mul_f32 v[18:19], v[26:27], v[38:39] op_sel_hi:[1,0]
	v_lshlrev_b32_e32 v20, 16, v57
	v_and_b32_e32 v21, 0xffff0000, v57
	v_pk_mul_f32 v[18:19], v[18:19], v[20:21]
	v_cvt_pk_bf16_f32 v244, v16, v17
	v_cvt_pk_bf16_f32 v245, v18, v19
	v_pk_mul_f32 v[16:17], v[28:29], v[38:39] op_sel_hi:[1,0]
	s_waitcnt vmcnt(5)
	v_lshlrev_b32_e32 v18, 16, v46
	v_and_b32_e32 v19, 0xffff0000, v46
	v_pk_mul_f32 v[16:17], v[16:17], v[18:19]
	v_pk_mul_f32 v[18:19], v[30:31], v[38:39] op_sel_hi:[1,0]
	v_lshlrev_b32_e32 v20, 16, v47
	v_and_b32_e32 v21, 0xffff0000, v47
	v_pk_mul_f32 v[18:19], v[18:19], v[20:21]
	v_cvt_pk_bf16_f32 v246, v16, v17
	v_cvt_pk_bf16_f32 v247, v18, v19
	s_nop 1
	v_permlane32_swap_b32_e32 v244, v246
	v_permlane32_swap_b32_e32 v245, v247
	global_store_dwordx4 v[242:243], v[244:247], off offset:32
	s_waitcnt vmcnt(5)
	v_lshlrev_b32_e32 v16, 16, v44
	v_and_b32_e32 v17, 0xffff0000, v44
	v_pk_mul_f32 v[0:1], v[0:1], v[16:17]
	v_lshlrev_b32_e32 v16, 16, v45
	v_and_b32_e32 v17, 0xffff0000, v45
	v_pk_mul_f32 v[2:3], v[2:3], v[16:17]
	v_cvt_pk_bf16_f32 v244, v0, v1
	v_cvt_pk_bf16_f32 v245, v2, v3
	v_pk_mul_f32 v[0:1], v[4:5], v[38:39] op_sel_hi:[1,0]
	s_waitcnt vmcnt(4)
	v_lshlrev_b32_e32 v2, 16, v36
	v_and_b32_e32 v3, 0xffff0000, v36
	v_pk_mul_f32 v[0:1], v[0:1], v[2:3]
	v_pk_mul_f32 v[2:3], v[6:7], v[38:39] op_sel_hi:[1,0]
	v_lshlrev_b32_e32 v4, 16, v37
	v_and_b32_e32 v5, 0xffff0000, v37
	v_pk_mul_f32 v[2:3], v[2:3], v[4:5]
	v_cvt_pk_bf16_f32 v246, v0, v1
	v_cvt_pk_bf16_f32 v247, v2, v3
	s_nop 1
	v_permlane32_swap_b32_e32 v244, v246
	v_permlane32_swap_b32_e32 v245, v247
	global_store_dwordx4 v[242:243], v[244:247], off offset:64
	v_pk_mul_f32 v[0:1], v[8:9], v[38:39] op_sel_hi:[1,0]
	s_waitcnt vmcnt(4)
	v_lshlrev_b32_e32 v2, 16, v32
	v_and_b32_e32 v3, 0xffff0000, v32
	v_pk_mul_f32 v[0:1], v[0:1], v[2:3]
	v_pk_mul_f32 v[2:3], v[10:11], v[38:39] op_sel_hi:[1,0]
	v_lshlrev_b32_e32 v4, 16, v33
	v_and_b32_e32 v5, 0xffff0000, v33
	v_pk_mul_f32 v[2:3], v[2:3], v[4:5]
	v_cvt_pk_bf16_f32 v244, v0, v1
	v_cvt_pk_bf16_f32 v245, v2, v3
	v_pk_mul_f32 v[0:1], v[12:13], v[38:39] op_sel_hi:[1,0]
	s_waitcnt vmcnt(3)
	v_lshlrev_b32_e32 v2, 16, v34
	v_and_b32_e32 v3, 0xffff0000, v34
	v_pk_mul_f32 v[0:1], v[0:1], v[2:3]
	v_pk_mul_f32 v[2:3], v[14:15], v[38:39] op_sel_hi:[1,0]
	v_lshlrev_b32_e32 v4, 16, v35
	v_and_b32_e32 v5, 0xffff0000, v35
	v_pk_mul_f32 v[2:3], v[2:3], v[4:5]
	v_cvt_pk_bf16_f32 v246, v0, v1
	v_cvt_pk_bf16_f32 v247, v2, v3
	s_nop 1
	v_permlane32_swap_b32_e32 v244, v246
	v_permlane32_swap_b32_e32 v245, v247
	global_store_dwordx4 v[242:243], v[244:247], off offset:96
	s_mov_b32 s65, 0
	s_barrier
	s_cbranch_scc1 .LBB0_895
